# P1 memory K/V sample GEMM (<4,4>): coalesced operand loads + ds_bpermute inserted by dataflow before the first MFMA use
# baseline (speedup 1.0000x reference)
.LBB0_337:
	s_or_b64 exec, exec, s[10:11]
	v_and_b32_e32 v154, 63, v204
	v_lshrrev_b32_e32 v155, 2, v154
	v_and_b32_e32 v156, 15, v154
	v_lshlrev_b32_e32 v153, 2, v156
	v_lshrrev_b32_e32 v157, 4, v154
	v_add_u32_e32 v153, v153, v157
	v_lshlrev_b32_e32 v153, 2, v153
	v_sub_u32_e32 v155, v155, v156
	v_lshlrev_b32_e32 v155, 11, v155
	v_and_b32_e32 v156, 3, v154
	v_lshlrev_b32_e32 v156, 4, v156
	v_and_b32_e32 v157, 48, v154
	v_sub_u32_e32 v156, v156, v157
	v_add_u32_e32 v154, v155, v156
	v_ashrrev_i32_e32 v155, 31, v154
	v_add_u32_e32 v34, s28, v27
	v_ashrrev_i32_e32 v35, 31, v34
	v_lshlrev_b64 v[34:35], 11, v[34:35]
	v_lshl_add_u64 v[132:133], v[2:3], 0, v[34:35]
	v_lshl_add_u64 v[132:133], v[132:133], 0, v[154:155]
	v_add_co_u32_e32 v134, vcc, 0x8000, v132
	s_lshl_b32 s29, s29, 6
	s_nop 0
	v_addc_co_u32_e32 v135, vcc, 0, v133, vcc
	v_or_b32_e32 v30, s29, v7
	v_add_co_u32_e32 v138, vcc, s24, v132
	v_ashrrev_i32_e32 v31, 31, v30
	s_nop 0
	v_addc_co_u32_e32 v139, vcc, 0, v133, vcc
	v_lshlrev_b64 v[30:31], 11, v[30:31]
	v_add_co_u32_e32 v146, vcc, s25, v132
	v_lshl_add_u64 v[130:131], v[4:5], 0, v[30:31]
	v_lshl_add_u64 v[130:131], v[130:131], 0, v[154:155]
	s_nop 0
	v_addc_co_u32_e32 v147, vcc, 0, v133, vcc
	v_add_co_u32_e32 v136, vcc, 0x8000, v130
	global_load_dwordx4 v[30:33], v[130:131], off
	global_load_dwordx4 v[34:37], v[132:133], off
	v_addc_co_u32_e32 v137, vcc, 0, v131, vcc
	v_add_co_u32_e32 v140, vcc, s24, v130
	global_load_dwordx4 v[38:41], v[132:133], off offset:64
	s_nop 0
	v_addc_co_u32_e32 v141, vcc, 0, v131, vcc
	v_add_co_u32_e32 v142, vcc, s25, v130
	global_load_dwordx4 v[42:45], v[130:131], off offset:64
	global_load_dwordx4 v[46:49], v[134:135], off
	global_load_dwordx4 v[50:53], v[138:139], off
	v_addc_co_u32_e32 v143, vcc, 0, v131, vcc
	global_load_dwordx4 v[58:61], v[146:147], off
	global_load_dwordx4 v[62:65], v[134:135], off offset:64
	global_load_dwordx4 v[70:73], v[138:139], off offset:64
	global_load_dwordx4 v[78:81], v[146:147], off offset:64
	global_load_dwordx4 v[82:85], v[136:137], off
	global_load_dwordx4 v[86:89], v[136:137], off offset:64
	global_load_dwordx4 v[102:105], v[140:141], off
	global_load_dwordx4 v[106:109], v[140:141], off offset:64
	global_load_dwordx4 v[122:125], v[142:143], off
	global_load_dwordx4 v[126:129], v[142:143], off offset:64
	s_waitcnt vmcnt(0)
	s_and_saveexec_b64 s[10:11], s[4:5]
	v_ffbh_u32_e32 v152, v149
	v_min_u32_e32 v152, 32, v152
	v_lshlrev_b64 v[148:149], v152, v[148:149]
	v_min_u32_e32 v148, 1, v148
	v_or_b32_e32 v148, v149, v148
	v_cvt_f32_u32_e32 v148, v148
	v_sub_u32_e32 v149, 32, v152
	v_ldexp_f32 v148, v148, v149
	v_fmamk_f32 v148, v148, 0x30800000, v28
	v_mul_f32_e32 v149, 0x4b800000, v148
	v_cmp_gt_f32_e32 vcc, s27, v148
	s_nop 1
	v_cndmask_b32_e32 v148, v148, v149, vcc
	v_rsq_f32_e32 v148, v148
	s_nop 0
	v_mul_f32_e32 v149, 0x45800000, v148
	v_cndmask_b32_e32 v10, v148, v149, vcc
	s_or_b64 exec, exec, s[10:11]
	s_and_saveexec_b64 s[10:11], s[6:7]
	v_ffbh_u32_e32 v152, v151
	v_min_u32_e32 v152, 32, v152
	v_lshlrev_b64 v[150:151], v152, v[150:151]
	v_min_u32_e32 v150, 1, v150
	v_or_b32_e32 v150, v151, v150
	v_cvt_f32_u32_e32 v150, v150
	v_sub_u32_e32 v151, 32, v152
	v_ldexp_f32 v150, v150, v151
	v_fmamk_f32 v150, v150, 0x30800000, v28
	v_mul_f32_e32 v151, 0x4b800000, v150
	v_cmp_gt_f32_e32 vcc, s27, v150
	s_nop 1
	v_cndmask_b32_e32 v150, v150, v151, vcc
	v_rsq_f32_e32 v150, v150
	s_nop 0
	v_mul_f32_e32 v151, 0x45800000, v150
	v_cndmask_b32_e32 v6, v150, v151, vcc
	s_or_b64 exec, exec, s[10:11]
	ds_bpermute_b32 v30, v153, v30
	ds_bpermute_b32 v31, v153, v31
	ds_bpermute_b32 v32, v153, v32
	ds_bpermute_b32 v33, v153, v33
	ds_bpermute_b32 v34, v153, v34
	ds_bpermute_b32 v35, v153, v35
	ds_bpermute_b32 v36, v153, v36
	ds_bpermute_b32 v37, v153, v37
	s_waitcnt lgkmcnt(0)
	v_mfma_f32_16x16x32_bf16 v[54:57], v[30:33], v[34:37], 0
	ds_bpermute_b32 v46, v153, v46
	ds_bpermute_b32 v47, v153, v47
	ds_bpermute_b32 v48, v153, v48
	ds_bpermute_b32 v49, v153, v49
	s_waitcnt lgkmcnt(0)
	v_mfma_f32_16x16x32_bf16 v[66:69], v[30:33], v[46:49], 0
	ds_bpermute_b32 v50, v153, v50
	ds_bpermute_b32 v51, v153, v51
	ds_bpermute_b32 v52, v153, v52
	ds_bpermute_b32 v53, v153, v53
	s_waitcnt lgkmcnt(0)
	v_mfma_f32_16x16x32_bf16 v[74:77], v[30:33], v[50:53], 0
	ds_bpermute_b32 v58, v153, v58
	ds_bpermute_b32 v59, v153, v59
	ds_bpermute_b32 v60, v153, v60
	ds_bpermute_b32 v61, v153, v61
	s_waitcnt lgkmcnt(0)
	v_mfma_f32_16x16x32_bf16 v[30:33], v[30:33], v[58:61], 0
	ds_bpermute_b32 v82, v153, v82
	ds_bpermute_b32 v83, v153, v83
	ds_bpermute_b32 v84, v153, v84
	ds_bpermute_b32 v85, v153, v85
	s_waitcnt lgkmcnt(0)
	v_mfma_f32_16x16x32_bf16 v[90:93], v[82:85], v[34:37], 0
	v_mfma_f32_16x16x32_bf16 v[94:97], v[82:85], v[46:49], 0
	v_mfma_f32_16x16x32_bf16 v[98:101], v[82:85], v[50:53], 0
	v_mfma_f32_16x16x32_bf16 v[82:85], v[82:85], v[58:61], 0
	ds_bpermute_b32 v42, v153, v42
	ds_bpermute_b32 v43, v153, v43
	ds_bpermute_b32 v44, v153, v44
	ds_bpermute_b32 v45, v153, v45
	ds_bpermute_b32 v38, v153, v38
	ds_bpermute_b32 v39, v153, v39
	ds_bpermute_b32 v40, v153, v40
	ds_bpermute_b32 v41, v153, v41
	s_waitcnt lgkmcnt(0)
	v_mfma_f32_16x16x32_bf16 v[54:57], v[42:45], v[38:41], v[54:57]
	ds_bpermute_b32 v62, v153, v62
	ds_bpermute_b32 v63, v153, v63
	ds_bpermute_b32 v64, v153, v64
	ds_bpermute_b32 v65, v153, v65
	s_waitcnt lgkmcnt(0)
	v_mfma_f32_16x16x32_bf16 v[66:69], v[42:45], v[62:65], v[66:69]
	ds_bpermute_b32 v70, v153, v70
	ds_bpermute_b32 v71, v153, v71
	ds_bpermute_b32 v72, v153, v72
	ds_bpermute_b32 v73, v153, v73
	s_waitcnt lgkmcnt(0)
	v_mfma_f32_16x16x32_bf16 v[74:77], v[42:45], v[70:73], v[74:77]
	ds_bpermute_b32 v78, v153, v78
	ds_bpermute_b32 v79, v153, v79
	ds_bpermute_b32 v80, v153, v80
	ds_bpermute_b32 v81, v153, v81
	s_waitcnt lgkmcnt(0)
	v_mfma_f32_16x16x32_bf16 v[30:33], v[42:45], v[78:81], v[30:33]
	ds_bpermute_b32 v86, v153, v86
	ds_bpermute_b32 v87, v153, v87
	ds_bpermute_b32 v88, v153, v88
	ds_bpermute_b32 v89, v153, v89
	s_waitcnt lgkmcnt(0)
	v_mfma_f32_16x16x32_bf16 v[42:45], v[86:89], v[78:81], v[82:85]
	s_nop 2
	global_load_dwordx4 v[82:85], v[130:131], off offset:128
	ds_bpermute_b32 v102, v153, v102
	ds_bpermute_b32 v103, v153, v103
	ds_bpermute_b32 v104, v153, v104
	ds_bpermute_b32 v105, v153, v105
	s_waitcnt lgkmcnt(0)
	v_mfma_f32_16x16x32_bf16 v[110:113], v[102:105], v[34:37], 0
	v_mfma_f32_16x16x32_bf16 v[114:117], v[102:105], v[46:49], 0
	v_mfma_f32_16x16x32_bf16 v[118:121], v[102:105], v[50:53], 0
	v_mfma_f32_16x16x32_bf16 v[102:105], v[102:105], v[58:61], 0
	ds_bpermute_b32 v122, v153, v122
	ds_bpermute_b32 v123, v153, v123
	ds_bpermute_b32 v124, v153, v124
	ds_bpermute_b32 v125, v153, v125
	s_waitcnt lgkmcnt(0)
	v_mfma_f32_16x16x32_bf16 v[34:37], v[122:125], v[34:37], 0
	v_mfma_f32_16x16x32_bf16 v[46:49], v[122:125], v[46:49], 0
	v_mfma_f32_16x16x32_bf16 v[50:53], v[122:125], v[50:53], 0
	v_mfma_f32_16x16x32_bf16 v[58:61], v[122:125], v[58:61], 0
	v_mfma_f32_16x16x32_bf16 v[90:93], v[86:89], v[38:41], v[90:93]
	v_mfma_f32_16x16x32_bf16 v[94:97], v[86:89], v[62:65], v[94:97]
	ds_bpermute_b32 v106, v153, v106
	ds_bpermute_b32 v107, v153, v107
	ds_bpermute_b32 v108, v153, v108
	ds_bpermute_b32 v109, v153, v109
	s_waitcnt lgkmcnt(0)
	v_mfma_f32_16x16x32_bf16 v[110:113], v[106:109], v[38:41], v[110:113]
	v_mfma_f32_16x16x32_bf16 v[114:117], v[106:109], v[62:65], v[114:117]
	ds_bpermute_b32 v126, v153, v126
	ds_bpermute_b32 v127, v153, v127
	ds_bpermute_b32 v128, v153, v128
	ds_bpermute_b32 v129, v153, v129
	s_waitcnt lgkmcnt(0)
	v_mfma_f32_16x16x32_bf16 v[34:37], v[126:129], v[38:41], v[34:37]
	v_mfma_f32_16x16x32_bf16 v[38:41], v[126:129], v[62:65], v[46:49]
	v_mfma_f32_16x16x32_bf16 v[46:49], v[86:89], v[70:73], v[98:101]
	v_mfma_f32_16x16x32_bf16 v[62:65], v[106:109], v[70:73], v[118:121]
	v_mfma_f32_16x16x32_bf16 v[50:53], v[126:129], v[70:73], v[50:53]
	v_mfma_f32_16x16x32_bf16 v[70:73], v[106:109], v[78:81], v[102:105]
	v_mfma_f32_16x16x32_bf16 v[58:61], v[126:129], v[78:81], v[58:61]
	global_load_dwordx4 v[78:81], v[132:133], off offset:128
	global_load_dwordx4 v[86:89], v[132:133], off offset:192
	global_load_dwordx4 v[98:101], v[130:131], off offset:192
	global_load_dwordx4 v[102:105], v[136:137], off offset:128
	global_load_dwordx4 v[106:109], v[136:137], off offset:192
	global_load_dwordx4 v[118:121], v[140:141], off offset:128
	global_load_dwordx4 v[122:125], v[140:141], off offset:192
	global_load_dwordx4 v[126:129], v[142:143], off offset:128
	global_load_dwordx4 v[130:133], v[142:143], off offset:192
	s_waitcnt vmcnt(8)
	ds_bpermute_b32 v82, v153, v82
	ds_bpermute_b32 v83, v153, v83
	ds_bpermute_b32 v84, v153, v84
	ds_bpermute_b32 v85, v153, v85
	ds_bpermute_b32 v78, v153, v78
	ds_bpermute_b32 v79, v153, v79
	ds_bpermute_b32 v80, v153, v80
	ds_bpermute_b32 v81, v153, v81
	s_waitcnt lgkmcnt(0)
	v_mfma_f32_16x16x32_bf16 v[54:57], v[82:85], v[78:81], v[54:57]
	s_waitcnt vmcnt(5)
	ds_bpermute_b32 v102, v153, v102
	ds_bpermute_b32 v103, v153, v103
	ds_bpermute_b32 v104, v153, v104
	ds_bpermute_b32 v105, v153, v105
	s_waitcnt lgkmcnt(0)
	v_mfma_f32_16x16x32_bf16 v[90:93], v[102:105], v[78:81], v[90:93]
	s_waitcnt vmcnt(3)
	ds_bpermute_b32 v118, v153, v118
	ds_bpermute_b32 v119, v153, v119
	ds_bpermute_b32 v120, v153, v120
	ds_bpermute_b32 v121, v153, v121
	s_waitcnt lgkmcnt(0)
	v_mfma_f32_16x16x32_bf16 v[110:113], v[118:121], v[78:81], v[110:113]
	s_waitcnt vmcnt(1)
	ds_bpermute_b32 v126, v153, v126
	ds_bpermute_b32 v127, v153, v127
	ds_bpermute_b32 v128, v153, v128
	ds_bpermute_b32 v129, v153, v129
	s_waitcnt lgkmcnt(0)
	v_mfma_f32_16x16x32_bf16 v[34:37], v[126:129], v[78:81], v[34:37]
	global_load_dwordx4 v[78:81], v[134:135], off offset:128
	s_nop 0
	global_load_dwordx4 v[134:137], v[134:135], off offset:192
	s_waitcnt vmcnt(1)
	ds_bpermute_b32 v78, v153, v78
	ds_bpermute_b32 v79, v153, v79
	ds_bpermute_b32 v80, v153, v80
	ds_bpermute_b32 v81, v153, v81
	s_waitcnt lgkmcnt(0)
	v_mfma_f32_16x16x32_bf16 v[66:69], v[82:85], v[78:81], v[66:69]
	v_mfma_f32_16x16x32_bf16 v[94:97], v[102:105], v[78:81], v[94:97]
	v_mfma_f32_16x16x32_bf16 v[114:117], v[118:121], v[78:81], v[114:117]
	v_mfma_f32_16x16x32_bf16 v[38:41], v[126:129], v[78:81], v[38:41]
	global_load_dwordx4 v[78:81], v[138:139], off offset:128
	s_nop 0
	global_load_dwordx4 v[138:141], v[138:139], off offset:192
	s_nop 0
	global_load_dwordx4 v[142:145], v[146:147], off offset:128
	s_waitcnt vmcnt(2)
	ds_bpermute_b32 v78, v153, v78
	ds_bpermute_b32 v79, v153, v79
	ds_bpermute_b32 v80, v153, v80
	ds_bpermute_b32 v81, v153, v81
	s_waitcnt lgkmcnt(0)
	v_mfma_f32_16x16x32_bf16 v[74:77], v[82:85], v[78:81], v[74:77]
	v_mfma_f32_16x16x32_bf16 v[46:49], v[102:105], v[78:81], v[46:49]
	v_mfma_f32_16x16x32_bf16 v[62:65], v[118:121], v[78:81], v[62:65]
	v_mfma_f32_16x16x32_bf16 v[50:53], v[126:129], v[78:81], v[50:53]
	global_load_dwordx4 v[78:81], v[146:147], off offset:192
	s_waitcnt vmcnt(1)
	ds_bpermute_b32 v142, v153, v142
	ds_bpermute_b32 v143, v153, v143
	ds_bpermute_b32 v144, v153, v144
	ds_bpermute_b32 v145, v153, v145
	s_waitcnt lgkmcnt(0)
	v_mfma_f32_16x16x32_bf16 v[30:33], v[82:85], v[142:145], v[30:33]
	v_mfma_f32_16x16x32_bf16 v[42:45], v[102:105], v[142:145], v[42:45]
	ds_bpermute_b32 v98, v153, v98
	ds_bpermute_b32 v99, v153, v99
	ds_bpermute_b32 v100, v153, v100
	ds_bpermute_b32 v101, v153, v101
	ds_bpermute_b32 v86, v153, v86
	ds_bpermute_b32 v87, v153, v87
	ds_bpermute_b32 v88, v153, v88
	ds_bpermute_b32 v89, v153, v89
	s_waitcnt lgkmcnt(0)
	v_mfma_f32_16x16x32_bf16 v[54:57], v[98:101], v[86:89], v[54:57]
	ds_bpermute_b32 v130, v153, v130
	ds_bpermute_b32 v131, v153, v131
	ds_bpermute_b32 v132, v153, v132
	ds_bpermute_b32 v133, v153, v133
	s_waitcnt lgkmcnt(0)
	v_mfma_f32_16x16x32_bf16 v[34:37], v[130:133], v[86:89], v[34:37]
	v_mfma_f32_16x16x32_bf16 v[70:73], v[118:121], v[142:145], v[70:73]
	ds_bpermute_b32 v106, v153, v106
	ds_bpermute_b32 v107, v153, v107
	ds_bpermute_b32 v108, v153, v108
	ds_bpermute_b32 v109, v153, v109
	s_waitcnt lgkmcnt(0)
	v_mfma_f32_16x16x32_bf16 v[82:85], v[106:109], v[86:89], v[90:93]
	ds_bpermute_b32 v122, v153, v122
	ds_bpermute_b32 v123, v153, v123
	ds_bpermute_b32 v124, v153, v124
	ds_bpermute_b32 v125, v153, v125
	s_waitcnt lgkmcnt(0)
	v_mfma_f32_16x16x32_bf16 v[90:93], v[122:125], v[86:89], v[110:113]
	s_nop 3
	ds_write_b128 v29, v[54:57]
	s_nop 1
	ds_write_b128 v29, v[82:85] offset:1024
	ds_write_b128 v29, v[90:93] offset:2048
	ds_bpermute_b32 v134, v153, v134
	ds_bpermute_b32 v135, v153, v135
	ds_bpermute_b32 v136, v153, v136
	ds_bpermute_b32 v137, v153, v137
	s_waitcnt lgkmcnt(0)
	v_mfma_f32_16x16x32_bf16 v[66:69], v[98:101], v[134:137], v[66:69]
	v_mfma_f32_16x16x32_bf16 v[86:89], v[106:109], v[134:137], v[94:97]
	ds_write_b128 v29, v[34:37] offset:3072
	s_nop 5
	ds_write_b128 v29, v[66:69] offset:4096
	ds_write_b128 v29, v[86:89] offset:5120
	v_mfma_f32_16x16x32_bf16 v[94:97], v[122:125], v[134:137], v[114:117]
	v_mfma_f32_16x16x32_bf16 v[38:41], v[130:133], v[134:137], v[38:41]
	v_mfma_f32_16x16x32_bf16 v[58:61], v[126:129], v[142:145], v[58:61]
	ds_bpermute_b32 v138, v153, v138
	ds_bpermute_b32 v139, v153, v139
	ds_bpermute_b32 v140, v153, v140
	ds_bpermute_b32 v141, v153, v141
	s_waitcnt lgkmcnt(0)
	v_mfma_f32_16x16x32_bf16 v[74:77], v[98:101], v[138:141], v[74:77]
	s_nop 4
	ds_write_b128 v29, v[94:97] offset:6144
	ds_write_b128 v29, v[38:41] offset:7168
	s_nop 0
	ds_write_b128 v29, v[74:77] offset:8192
	v_mfma_f32_16x16x32_bf16 v[46:49], v[106:109], v[138:141], v[46:49]
	s_waitcnt vmcnt(0)
	ds_bpermute_b32 v78, v153, v78
	ds_bpermute_b32 v79, v153, v79
	ds_bpermute_b32 v80, v153, v80
	ds_bpermute_b32 v81, v153, v81
	s_waitcnt lgkmcnt(0)
	v_mfma_f32_16x16x32_bf16 v[30:33], v[98:101], v[78:81], v[30:33]
	v_mfma_f32_16x16x32_bf16 v[62:65], v[122:125], v[138:141], v[62:65]
	v_mfma_f32_16x16x32_bf16 v[34:37], v[106:109], v[78:81], v[42:45]
	v_mfma_f32_16x16x32_bf16 v[50:53], v[130:133], v[138:141], v[50:53]
	s_nop 2
	ds_write_b128 v29, v[46:49] offset:9216
	s_nop 1
	ds_write_b128 v29, v[62:65] offset:10240
	s_nop 0
	ds_write_b128 v29, v[50:53] offset:11264
	v_mfma_f32_16x16x32_bf16 v[38:41], v[122:125], v[78:81], v[70:73]
	ds_write_b128 v29, v[30:33] offset:12288
	ds_write_b128 v29, v[34:37] offset:13312
	s_nop 5
	ds_write_b128 v29, v[38:41] offset:14336
	v_mfma_f32_16x16x32_bf16 v[30:33], v[130:133], v[78:81], v[58:61]
	s_nop 7
	ds_write_b128 v29, v[30:33] offset:15360
	s_waitcnt lgkmcnt(0)
	s_barrier
	s_and_saveexec_b64 s[10:11], s[4:5]
	s_cbranch_execz .LBB0_332
	ds_read_b128 v[30:33], v15 offset:16384
	ds_read_b128 v[34:37], v14
	ds_read_b128 v[38:41], v15 offset:32768
	ds_read_b128 v[42:45], v15 offset:49152
	s_waitcnt lgkmcnt(2)
	v_pk_add_f32 v[32:33], v[36:37], v[32:33]
	v_pk_add_f32 v[34:35], v[34:35], v[30:31]
	s_waitcnt lgkmcnt(1)
	v_pk_add_f32 v[36:37], v[32:33], v[40:41]
	ds_read_b128 v[30:33], v16
	v_pk_add_f32 v[34:35], v[34:35], v[38:39]
	s_waitcnt lgkmcnt(1)
	v_pk_add_f32 v[38:39], v[36:37], v[44:45]
	v_pk_add_f32 v[42:43], v[34:35], v[42:43]
	ds_read_b128 v[34:37], v17
	s_waitcnt lgkmcnt(1)
	v_pk_add_f32 v[44:45], v[38:39], v[32:33]
	ds_read_b128 v[38:41], v18
	v_pk_add_f32 v[42:43], v[42:43], v[30:31]
	ds_read_b128 v[30:33], v19
	s_waitcnt lgkmcnt(2)
	v_pk_add_f32 v[34:35], v[42:43], v[34:35]
	v_pk_add_f32 v[36:37], v[44:45], v[36:37]
	s_waitcnt lgkmcnt(1)
	v_pk_add_f32 v[34:35], v[34:35], v[38:39]
	v_pk_add_f32 v[36:37], v[36:37], v[40:41]
	s_waitcnt lgkmcnt(0)
	v_pk_add_f32 v[30:31], v[34:35], v[30:31]
	v_add_u32_e32 v34, s29, v20
	v_and_b32_e32 v0, 0x3f0, v34
	v_or_b32_e32 v35, v0, v11
	v_pk_add_f32 v[32:33], v[36:37], v[32:33]
	v_add_u32_e32 v36, 0xfffffe00, v35
	v_cmp_gt_u32_e32 vcc, s23, v0
	v_ashrrev_i32_e32 v34, 10, v34
	v_mov_b32_e32 v37, s13
	v_cndmask_b32_e32 v0, v36, v35, vcc
	v_mov_b32_e32 v36, s15
	v_ashrrev_i32_e32 v35, 31, v34
	v_cndmask_b32_e32 v37, v36, v37, vcc
	v_mov_b32_e32 v36, s14
	v_mov_b32_e32 v38, s12
	v_cndmask_b32_e32 v36, v36, v38, vcc
	v_lshlrev_b64 v[38:39], 20, v[34:35]
	v_lshl_add_u64 v[36:37], v[36:37], 0, v[38:39]
	v_lshlrev_b64 v[38:39], 11, v[8:9]
	v_lshl_add_u64 v[36:37], v[36:37], 0, v[38:39]
	v_pk_mul_f32 v[30:31], v[10:11], v[30:31] op_sel_hi:[0,1]
	v_pk_mul_f32 v[32:33], v[10:11], v[32:33] op_sel_hi:[0,1]
	v_lshl_add_u64 v[36:37], v[0:1], 2, v[36:37]
	v_mov_b32_e32 v10, s22
	v_mov_b32_e32 v35, s20
	global_store_dwordx4 v[36:37], v[30:33], off
	v_cndmask_b32_e32 v37, v10, v35, vcc
	v_mov_b32_e32 v10, s21
	v_mov_b32_e32 v35, s19
	v_cndmask_b32_e32 v36, v10, v35, vcc
	v_mul_hi_i32_i24_e32 v35, 0x280000, v34
	v_mul_i32_i24_e32 v34, 0x280000, v34
	v_lshl_add_u64 v[34:35], v[36:37], 0, v[34:35]
	v_lshlrev_b64 v[8:9], 10, v[8:9]
	v_lshl_add_u64 v[8:9], v[34:35], 0, v[8:9]
	v_lshl_add_u64 v[8:9], v[0:1], 1, v[8:9]
	v_cvt_pk_bf16_f32 v30, v30, v31
	v_cvt_pk_bf16_f32 v31, v32, v33
	global_store_dwordx2 v[8:9], v[30:31], off
	s_and_b64 exec, exec, s[6:7]
	s_cbranch_execz .LBB0_332
	ds_read_b128 v[30:33], v21 offset:16384
	ds_read_b128 v[34:37], v14 offset:8192
	ds_read_b128 v[38:41], v21 offset:32768
	ds_read_b128 v[42:45], v21 offset:49152
	v_add_u32_e32 v10, s29, v26
	v_and_b32_e32 v0, 0x3f0, v10
	s_waitcnt lgkmcnt(2)
	v_pk_add_f32 v[8:9], v[36:37], v[32:33]
	v_pk_add_f32 v[34:35], v[34:35], v[30:31]
	ds_read_b128 v[30:33], v22
	s_waitcnt lgkmcnt(2)
	v_pk_add_f32 v[34:35], v[34:35], v[38:39]
	v_pk_add_f32 v[8:9], v[8:9], v[40:41]
	s_waitcnt lgkmcnt(1)
	v_pk_add_f32 v[42:43], v[34:35], v[42:43]
	ds_read_b128 v[34:37], v23
	v_pk_add_f32 v[8:9], v[8:9], v[44:45]
	ds_read_b128 v[38:41], v24
	s_waitcnt lgkmcnt(2)
	v_pk_add_f32 v[8:9], v[8:9], v[32:33]
	v_pk_add_f32 v[42:43], v[42:43], v[30:31]
	ds_read_b128 v[30:33], v25
	s_waitcnt lgkmcnt(2)
	v_pk_add_f32 v[8:9], v[8:9], v[36:37]
	v_pk_add_f32 v[34:35], v[42:43], v[34:35]
	s_waitcnt lgkmcnt(1)
	v_pk_add_f32 v[8:9], v[8:9], v[40:41]
	v_cmp_gt_u32_e32 vcc, s23, v0
	s_waitcnt lgkmcnt(0)
	v_pk_add_f32 v[8:9], v[8:9], v[32:33]
	v_or_b32_e32 v32, v0, v11
	v_add_u32_e32 v33, 0xfffffe00, v32
	v_pk_add_f32 v[34:35], v[34:35], v[38:39]
	v_cndmask_b32_e32 v0, v33, v32, vcc
	v_ashrrev_i32_e32 v36, 10, v10
	v_mov_b32_e32 v10, s15
	v_mov_b32_e32 v32, s13
	v_pk_add_f32 v[30:31], v[34:35], v[30:31]
	v_add3_u32 v34, v13, v27, s28
	v_ashrrev_i32_e32 v37, 31, v36
	v_cndmask_b32_e32 v33, v10, v32, vcc
	v_mov_b32_e32 v10, s14
	v_mov_b32_e32 v32, s12
	v_ashrrev_i32_e32 v35, 31, v34
	v_cndmask_b32_e32 v32, v10, v32, vcc
	v_lshlrev_b64 v[38:39], 20, v[36:37]
	v_lshl_add_u64 v[32:33], v[32:33], 0, v[38:39]
	v_lshlrev_b64 v[38:39], 11, v[34:35]
	v_lshl_add_u64 v[38:39], v[32:33], 0, v[38:39]
	v_pk_mul_f32 v[30:31], v[6:7], v[30:31] op_sel_hi:[0,1]
	v_pk_mul_f32 v[32:33], v[6:7], v[8:9] op_sel_hi:[0,1]
	v_lshl_add_u64 v[8:9], v[0:1], 2, v[38:39]
	global_store_dwordx4 v[8:9], v[30:33], off
	v_mov_b32_e32 v6, s22
	v_mov_b32_e32 v8, s20
	v_cndmask_b32_e32 v9, v6, v8, vcc
	v_mov_b32_e32 v6, s21
	v_mov_b32_e32 v8, s19
	v_cndmask_b32_e32 v8, v6, v8, vcc
	v_mul_hi_i32_i24_e32 v37, 0x280000, v36
	v_mul_i32_i24_e32 v36, 0x280000, v36
	v_lshl_add_u64 v[8:9], v[8:9], 0, v[36:37]
	v_lshlrev_b64 v[34:35], 10, v[34:35]
	v_lshl_add_u64 v[8:9], v[8:9], 0, v[34:35]
	v_lshl_add_u64 v[8:9], v[0:1], 1, v[8:9]
	v_cvt_pk_bf16_f32 v30, v30, v31
	v_cvt_pk_bf16_f32 v31, v32, v33
	global_store_dwordx2 v[8:9], v[30:31], off
	s_branch .LBB0_332
